# U pass 8-lane reduce via DPP (row_ror / quad_perm adds) instead of cndmask+ds_bpermute+add groups; V pass reduce level 8 via DPP row_ror:8; integer and f32 sums bit-identical
# speedup vs baseline: 1.0231x; 1.0122x over previous
.Lux_skip1:
	v_dot4c_i32_i8_e32 v138, v0, v64
	v_dot4c_i32_i8_e32 v178, v4, v64
	v_dot4c_i32_i8_e32 v185, v32, v64
	v_dot4c_i32_i8_e32 v186, v36, v64
	v_dot4c_i32_i8_e32 v138, v1, v65
	v_lshl_or_b32 v69, v69, 7, v137
	v_lshl_or_b32 v68, v68, 7, v174
	global_load_dwordx4 v[132:135], v68, s[14:15]
	global_load_dwordx4 v[128:131], v69, s[14:15]
	v_dot4c_i32_i8_e32 v178, v5, v65
	v_dot4c_i32_i8_e32 v185, v33, v65
	v_dot4c_i32_i8_e32 v186, v37, v65
	v_dot4c_i32_i8_e32 v138, v2, v66
	v_dot4c_i32_i8_e32 v178, v6, v66
	v_dot4c_i32_i8_e32 v185, v34, v66
	v_dot4c_i32_i8_e32 v186, v38, v66
	v_dot4c_i32_i8_e32 v138, v3, v67
	v_dot4c_i32_i8_e32 v178, v7, v67
	v_dot4c_i32_i8_e32 v185, v35, v67
	v_dot4c_i32_i8_e32 v186, v39, v67
	v_lshl_or_b32 v69, v70, 7, v174
	v_lshl_or_b32 v68, v71, 7, v137
	global_load_dwordx4 v[124:127], v69, s[14:15]
	global_load_dwordx4 v[120:123], v68, s[14:15]
	v_add_u32_dpp v215, v138, v138 row_ror:12 row_mask:0xf bank_mask:0x5
	v_add_u32_dpp v215, v185, v185 row_ror:4 row_mask:0xf bank_mask:0xa
	v_dot4_i32_i8 v180, v12, v64, 0
	v_dot4_i32_i8 v210, v44, v64, 0
	v_dot4c_i32_i8_e32 v180, v13, v65
	v_dot4_i32_i8 v181, v16, v64, 0
	v_lshl_or_b32 v69, v72, 7, v174
	v_lshl_or_b32 v68, v73, 7, v137
	global_load_dwordx4 v[116:119], v69, s[14:15]
	global_load_dwordx4 v[112:115], v68, s[14:15]
	v_dot4c_i32_i8_e32 v210, v45, v65
	v_dot4_i32_i8 v211, v48, v64, 0
	v_dot4c_i32_i8_e32 v180, v14, v66
	v_dot4c_i32_i8_e32 v181, v17, v65
	v_dot4c_i32_i8_e32 v210, v46, v66
	v_dot4c_i32_i8_e32 v211, v49, v65
	v_dot4c_i32_i8_e32 v180, v15, v67
	v_dot4c_i32_i8_e32 v181, v18, v66
	v_dot4c_i32_i8_e32 v210, v47, v67
	v_dot4c_i32_i8_e32 v211, v50, v66
	v_add_u32_dpp v178, v178, v178 row_ror:12 row_mask:0xf bank_mask:0x5
	v_add_u32_dpp v178, v186, v186 row_ror:4 row_mask:0xf bank_mask:0xa
	v_lshl_or_b32 v69, v74, 7, v174
	v_lshl_or_b32 v68, v75, 7, v137
	global_load_dwordx4 v[108:111], v69, s[14:15]
	global_load_dwordx4 v[104:107], v68, s[14:15]
	v_dot4c_i32_i8_e32 v181, v19, v67
	v_dot4c_i32_i8_e32 v211, v51, v67
	s_waitcnt lgkmcnt(0)
	v_add_u32_dpp v185, v180, v180 row_ror:12 row_mask:0xf bank_mask:0x5
	v_add_u32_dpp v185, v210, v210 row_ror:4 row_mask:0xf bank_mask:0xa
	v_dot4_i32_i8 v179, v8, v64, 0
	v_dot4_i32_i8 v182, v20, v64, 0
	v_lshl_or_b32 v69, v76, 7, v174
	v_lshl_or_b32 v68, v77, 7, v137
	global_load_dwordx4 v[100:103], v69, s[14:15]
	global_load_dwordx4 v[96:99], v68, s[14:15]
	v_dot4_i32_i8 v187, v40, v64, 0
	v_dot4_i32_i8 v212, v52, v64, 0
	v_dot4c_i32_i8_e32 v179, v9, v65
	v_dot4c_i32_i8_e32 v182, v21, v65
	v_dot4_i32_i8 v183, v24, v64, 0
	v_dot4c_i32_i8_e32 v187, v41, v65
	v_lshl_or_b32 v69, v78, 7, v174
	v_lshl_or_b32 v68, v79, 7, v137
	global_load_dwordx4 v[92:95], v69, s[14:15]
	global_load_dwordx4 v[88:91], v68, s[14:15]
	v_dot4c_i32_i8_e32 v212, v53, v65
	v_dot4_i32_i8 v213, v56, v64, 0
	v_dot4c_i32_i8_e32 v179, v10, v66
	v_dot4c_i32_i8_e32 v182, v22, v66
	v_dot4c_i32_i8_e32 v183, v25, v65
	v_dot4_i32_i8 v184, v28, v64, 0
	v_dot4c_i32_i8_e32 v187, v42, v66
	v_dot4c_i32_i8_e32 v212, v54, v66
	v_dot4c_i32_i8_e32 v213, v57, v65
	v_lshl_or_b32 v68, v81, 7, v137
	v_lshl_or_b32 v69, v80, 7, v174
	global_load_dwordx4 v[84:87], v69, s[14:15]
	global_load_dwordx4 v[76:79], v68, s[14:15]
	v_dot4_i32_i8 v214, v60, v64, 0
	v_dot4c_i32_i8_e32 v179, v11, v67
	v_dot4c_i32_i8_e32 v182, v23, v67
	v_dot4c_i32_i8_e32 v183, v26, v66
	v_dot4c_i32_i8_e32 v184, v29, v65
	v_dot4c_i32_i8_e32 v187, v43, v67
	v_dot4c_i32_i8_e32 v212, v55, v67
	v_dot4c_i32_i8_e32 v213, v58, v66
	v_dot4c_i32_i8_e32 v214, v61, v65
	v_dot4c_i32_i8_e32 v183, v27, v67
	v_dot4c_i32_i8_e32 v184, v30, v66
	v_dot4c_i32_i8_e32 v213, v59, v67
	v_lshl_or_b32 v68, v83, 7, v137
	v_lshl_or_b32 v69, v82, 7, v174
	global_load_dwordx4 v[72:75], v69, s[14:15]
	global_load_dwordx4 v[68:71], v68, s[14:15]
	v_add_u32_e32 v231, s99, v230
	ds_read_b128 v[80:83], v231
	v_dot4c_i32_i8_e32 v214, v62, v66
	v_add_u32_dpp v179, v179, v179 row_ror:12 row_mask:0xf bank_mask:0x5
	v_add_u32_dpp v179, v187, v187 row_ror:4 row_mask:0xf bank_mask:0xa
	v_dot4c_i32_i8_e32 v184, v31, v67
	v_dot4c_i32_i8_e32 v214, v63, v67
	s_waitcnt lgkmcnt(3)
	v_mov_b32_e32 v180, v185
	v_add_u32_dpp v181, v181, v181 row_ror:12 row_mask:0xf bank_mask:0x5
	v_add_u32_dpp v181, v211, v211 row_ror:4 row_mask:0xf bank_mask:0xa
	v_add_u32_dpp v185, v183, v183 row_ror:12 row_mask:0xf bank_mask:0x5
	v_add_u32_dpp v185, v213, v213 row_ror:4 row_mask:0xf bank_mask:0xa
	s_waitcnt lgkmcnt(3)
	v_add_u32_dpp v182, v182, v182 row_ror:12 row_mask:0xf bank_mask:0x5
	v_add_u32_dpp v182, v212, v212 row_ror:4 row_mask:0xf bank_mask:0xa
	s_waitcnt lgkmcnt(4)
	v_mov_b32_e32 v138, v215
	s_waitcnt lgkmcnt(3)
	s_waitcnt lgkmcnt(2)
	s_waitcnt lgkmcnt(1)
	v_mov_b32_e32 v183, v185
	v_add_u32_dpp v184, v184, v184 row_ror:12 row_mask:0xf bank_mask:0x5
	v_add_u32_dpp v184, v214, v214 row_ror:4 row_mask:0xf bank_mask:0xa
	v_add_u32_dpp v234, v138, v138 quad_perm:[2,3,0,1] row_mask:0xf bank_mask:0xf
	v_add_u32_dpp v235, v181, v181 quad_perm:[2,3,0,1] row_mask:0xf bank_mask:0xf
	v_cndmask_b32_e64 v138, v235, v234, s[4:5]
	v_add_u32_dpp v234, v178, v178 quad_perm:[2,3,0,1] row_mask:0xf bank_mask:0xf
	v_add_u32_dpp v235, v182, v182 quad_perm:[2,3,0,1] row_mask:0xf bank_mask:0xf
	v_cndmask_b32_e64 v181, v235, v234, s[4:5]
	s_waitcnt lgkmcnt(0)
	s_waitcnt lgkmcnt(3)
	v_add_u32_dpp v234, v179, v179 quad_perm:[2,3,0,1] row_mask:0xf bank_mask:0xf
	v_add_u32_dpp v235, v183, v183 quad_perm:[2,3,0,1] row_mask:0xf bank_mask:0xf
	v_cndmask_b32_e64 v178, v235, v234, s[4:5]
	s_waitcnt lgkmcnt(2)
	s_waitcnt lgkmcnt(1)
	v_add_u32_dpp v234, v180, v180 quad_perm:[2,3,0,1] row_mask:0xf bank_mask:0xf
	v_add_u32_dpp v235, v184, v184 quad_perm:[2,3,0,1] row_mask:0xf bank_mask:0xf
	v_cndmask_b32_e64 v179, v235, v234, s[4:5]
	s_waitcnt lgkmcnt(0)
	s_add_i32 s1, s61, 0xffffff00
	v_add_u32_dpp v234, v138, v138 quad_perm:[1,0,3,2] row_mask:0xf bank_mask:0xf
	v_add_u32_dpp v235, v178, v178 quad_perm:[1,0,3,2] row_mask:0xf bank_mask:0xf
	v_cndmask_b32_e64 v138, v235, v234, s[6:7]
	s_and_b32 s1, s1, 0x700
	s_waitcnt lgkmcnt(1)
	v_mov_b32_e32 v178, v138
	v_add_u32_dpp v234, v181, v181 quad_perm:[1,0,3,2] row_mask:0xf bank_mask:0xf
	v_add_u32_dpp v235, v179, v179 quad_perm:[1,0,3,2] row_mask:0xf bank_mask:0xf
	v_cndmask_b32_e64 v138, v235, v234, s[6:7]
	s_cmp_gt_u32 s0, 15
	s_waitcnt lgkmcnt(0)
	v_mov_b32_e32 v179, v138
	s_cselect_b64 s[14:15], -1, 0
	s_cmp_lt_u32 s0, 16
	v_lshl_add_u32 v138, s1, 2, v190
	s_cbranch_scc1 .LBB0_926
	ds_read_b64 v[180:181], v138
	s_waitcnt lgkmcnt(0)
	v_add_u32_e32 v178, v180, v178
	v_add_u32_e32 v179, v181, v179

.LBB0_928:
	s_waitcnt vmcnt(0)
	v_dot4_i32_i8 v138, v132, v80, 0
	global_load_dwordx4 v[0:3], v0, s[16:17]
	v_dot4_i32_i8 v132, v128, v80, 0
	v_dot4_i32_i8 v128, v124, v80, 0
	v_dot4_i32_i8 v124, v120, v80, 0
	global_load_dwordx4 v[4:7], v4, s[16:17]
	v_dot4_i32_i8 v120, v116, v80, 0
	v_dot4_i32_i8 v116, v112, v80, 0
	global_load_dwordx4 v[8:11], v8, s[16:17]
	v_dot4_i32_i8 v112, v108, v80, 0
	v_dot4_i32_i8 v108, v104, v80, 0
	v_dot4_i32_i8 v104, v100, v80, 0
	global_load_dwordx4 v[12:15], v12, s[16:17]
	v_dot4_i32_i8 v100, v96, v80, 0
	v_dot4_i32_i8 v96, v92, v80, 0
	v_dot4_i32_i8 v92, v88, v80, 0
	global_load_dwordx4 v[16:19], v16, s[16:17]
	v_dot4_i32_i8 v88, v84, v80, 0
	v_dot4c_i32_i8_e32 v138, v133, v81
	v_dot4c_i32_i8_e32 v104, v101, v81
	global_load_dwordx4 v[20:23], v20, s[16:17]
	v_dot4_i32_i8 v84, v76, v80, 0
	v_dot4c_i32_i8_e32 v138, v134, v82
	v_dot4c_i32_i8_e32 v132, v129, v81
	v_dot4c_i32_i8_e32 v104, v102, v82
	global_load_dwordx4 v[24:27], v24, s[16:17]
	v_dot4c_i32_i8_e32 v100, v97, v81
	v_dot4_i32_i8 v76, v72, v80, 0
	v_dot4c_i32_i8_e32 v138, v135, v83
	v_dot4c_i32_i8_e32 v132, v130, v82
	global_load_dwordx4 v[28:31], v28, s[16:17]
	v_dot4c_i32_i8_e32 v128, v125, v81
	v_dot4c_i32_i8_e32 v104, v103, v83
	v_dot4c_i32_i8_e32 v100, v98, v82
	v_dot4c_i32_i8_e32 v96, v93, v81
	v_dot4_i32_i8 v72, v68, v80, 0
	global_load_dwordx4 v[32:35], v32, s[16:17]
	v_dot4c_i32_i8_e32 v132, v131, v83
	v_dot4c_i32_i8_e32 v128, v126, v82
	v_dot4c_i32_i8_e32 v124, v121, v81
	v_dot4c_i32_i8_e32 v100, v99, v83
	v_dot4c_i32_i8_e32 v96, v94, v82
	global_load_dwordx4 v[36:39], v36, s[16:17]
	v_dot4c_i32_i8_e32 v92, v89, v81
	v_dot4c_i32_i8_e32 v72, v69, v81
	v_dot4c_i32_i8_e32 v128, v127, v83
	v_dot4c_i32_i8_e32 v124, v122, v82
	global_load_dwordx4 v[40:43], v40, s[16:17]
	v_dot4c_i32_i8_e32 v120, v117, v81
	v_dot4c_i32_i8_e32 v96, v95, v83
	v_dot4c_i32_i8_e32 v92, v90, v82
	v_dot4c_i32_i8_e32 v88, v85, v81
	v_dot4c_i32_i8_e32 v72, v70, v82
	global_load_dwordx4 v[44:47], v44, s[16:17]
	v_dot4c_i32_i8_e32 v124, v123, v83
	v_dot4c_i32_i8_e32 v120, v118, v82
	v_dot4c_i32_i8_e32 v116, v113, v81
	global_load_dwordx4 v[48:51], v48, s[16:17]
	v_dot4c_i32_i8_e32 v92, v91, v83
	v_dot4c_i32_i8_e32 v88, v86, v82
	v_dot4c_i32_i8_e32 v84, v77, v81
	v_dot4c_i32_i8_e32 v72, v71, v83
	global_load_dwordx4 v[52:55], v52, s[16:17]
	v_dot4c_i32_i8_e32 v120, v119, v83
	v_dot4c_i32_i8_e32 v116, v114, v82
	v_dot4c_i32_i8_e32 v88, v87, v83
	v_dot4c_i32_i8_e32 v84, v78, v82
	v_dot4c_i32_i8_e32 v76, v73, v81
	global_load_dwordx4 v[56:59], v56, s[16:17]
	v_dot4c_i32_i8_e32 v116, v115, v83
	v_dot4c_i32_i8_e32 v84, v79, v83
	v_dot4c_i32_i8_e32 v76, v74, v82
	global_load_dwordx4 v[60:63], v60, s[16:17]
	v_dot4c_i32_i8_e32 v76, v75, v83
	v_add_u32_dpp v68, v138, v138 row_ror:12 row_mask:0xf bank_mask:0x5
	v_add_u32_dpp v68, v104, v104 row_ror:4 row_mask:0xf bank_mask:0xa
	s_waitcnt lgkmcnt(4)
	v_add_u32_dpp v69, v132, v132 row_ror:12 row_mask:0xf bank_mask:0x5
	v_add_u32_dpp v69, v100, v100 row_ror:4 row_mask:0xf bank_mask:0xa
	s_waitcnt lgkmcnt(4)
	v_add_u32_dpp v70, v128, v128 row_ror:12 row_mask:0xf bank_mask:0x5
	v_add_u32_dpp v70, v96, v96 row_ror:4 row_mask:0xf bank_mask:0xa
	v_dot4c_i32_i8_e32 v112, v109, v81
	v_dot4c_i32_i8_e32 v108, v105, v81
	s_waitcnt lgkmcnt(3)
	v_add_u32_dpp v71, v124, v124 row_ror:12 row_mask:0xf bank_mask:0x5
	v_add_u32_dpp v71, v92, v92 row_ror:4 row_mask:0xf bank_mask:0xa
	v_dot4c_i32_i8_e32 v112, v110, v82
	v_dot4c_i32_i8_e32 v108, v106, v82
	s_waitcnt lgkmcnt(2)
	v_add_u32_dpp v73, v120, v120 row_ror:12 row_mask:0xf bank_mask:0x5
	v_add_u32_dpp v73, v88, v88 row_ror:4 row_mask:0xf bank_mask:0xa
	v_dot4c_i32_i8_e32 v112, v111, v83
	v_dot4c_i32_i8_e32 v108, v107, v83
	s_waitcnt lgkmcnt(1)
	v_add_u32_dpp v74, v116, v116 row_ror:12 row_mask:0xf bank_mask:0x5
	v_add_u32_dpp v74, v84, v84 row_ror:4 row_mask:0xf bank_mask:0xa
	s_waitcnt lgkmcnt(0)
	v_add_u32_dpp v75, v112, v112 row_ror:12 row_mask:0xf bank_mask:0x5
	v_add_u32_dpp v75, v76, v76 row_ror:4 row_mask:0xf bank_mask:0xa
	v_add_u32_dpp v72, v72, v72 row_ror:4 row_mask:0xf bank_mask:0xa
	v_add_u32_dpp v72, v108, v108 row_ror:12 row_mask:0xf bank_mask:0x5
	v_add_u32_dpp v234, v68, v68 quad_perm:[2,3,0,1] row_mask:0xf bank_mask:0xf
	v_add_u32_dpp v235, v73, v73 quad_perm:[2,3,0,1] row_mask:0xf bank_mask:0xf
	v_cndmask_b32_e64 v68, v235, v234, s[4:5]
	s_waitcnt lgkmcnt(1)
	s_waitcnt lgkmcnt(0)
	v_add_u32_dpp v234, v69, v69 quad_perm:[2,3,0,1] row_mask:0xf bank_mask:0xf
	v_add_u32_dpp v235, v74, v74 quad_perm:[2,3,0,1] row_mask:0xf bank_mask:0xf
	v_cndmask_b32_e64 v73, v235, v234, s[4:5]
	v_add_u32_dpp v234, v70, v70 quad_perm:[2,3,0,1] row_mask:0xf bank_mask:0xf
	v_add_u32_dpp v235, v75, v75 quad_perm:[2,3,0,1] row_mask:0xf bank_mask:0xf
	v_cndmask_b32_e64 v70, v235, v234, s[4:5]
	v_add_u32_dpp v234, v71, v71 quad_perm:[2,3,0,1] row_mask:0xf bank_mask:0xf
	v_add_u32_dpp v235, v72, v72 quad_perm:[2,3,0,1] row_mask:0xf bank_mask:0xf
	v_cndmask_b32_e64 v71, v235, v234, s[4:5]
	s_waitcnt lgkmcnt(3)
	s_waitcnt lgkmcnt(2)
	v_mov_b32_e32 v69, v73
	s_waitcnt lgkmcnt(1)
	s_waitcnt lgkmcnt(0)
	v_add_u32_dpp v234, v68, v68 quad_perm:[1,0,3,2] row_mask:0xf bank_mask:0xf
	v_add_u32_dpp v235, v70, v70 quad_perm:[1,0,3,2] row_mask:0xf bank_mask:0xf
	v_cndmask_b32_e64 v68, v235, v234, s[6:7]
	v_add_u32_dpp v234, v69, v69 quad_perm:[1,0,3,2] row_mask:0xf bank_mask:0xf
	v_add_u32_dpp v235, v71, v71 quad_perm:[1,0,3,2] row_mask:0xf bank_mask:0xf
	v_cndmask_b32_e64 v69, v235, v234, s[6:7]
	s_andn2_b64 vcc, exec, s[14:15]
	s_waitcnt lgkmcnt(1)
	s_waitcnt lgkmcnt(0)
	v_lshl_add_u32 v70, s65, 2, v190
	s_cbranch_vccnz .LBB0_923
	ds_read_b64 v[72:73], v70
	s_waitcnt lgkmcnt(0)
	v_add_u32_e32 v68, v72, v68
	v_add_u32_e32 v69, v73, v69
	s_branch .LBB0_923

.Lvx_skip:
	v_pk_fma_f32 v[86:87], v[128:129], v[86:87], v[94:95] op_sel_hi:[0,1,1]
	v_pk_fma_f32 v[90:91], v[128:129], v[90:91], v[98:99] op_sel_hi:[0,1,1]
	v_pk_fma_f32 v[94:95], v[128:129], v[96:97], v[100:101] op_sel_hi:[0,1,1]
	v_pk_fma_f32 v[76:77], v[128:129], v[76:77], v[80:81] op_sel_hi:[0,1,1]
	v_cvt_pk_f32_fp8_e32 v[80:81], v78
	v_cvt_pk_f32_fp8_sdwa v[96:97], v78 src0_sel:WORD_1
	v_cvt_pk_f32_fp8_e32 v[98:99], v79
	v_cvt_pk_f32_fp8_sdwa v[78:79], v79 src0_sel:WORD_1
	v_pk_fma_f32 v[80:81], v[128:129], v[80:81], v[84:85] op_sel_hi:[0,1,1]
	v_pk_fma_f32 v[84:85], v[128:129], v[96:97], v[88:89] op_sel_hi:[0,1,1]
	v_pk_fma_f32 v[88:89], v[128:129], v[98:99], v[92:93] op_sel_hi:[0,1,1]
	v_pk_fma_f32 v[78:79], v[128:129], v[78:79], v[82:83] op_sel_hi:[0,1,1]
	v_cvt_pk_f32_fp8_e32 v[82:83], v72
	v_cvt_pk_f32_fp8_sdwa v[92:93], v72 src0_sel:WORD_1
	v_cvt_pk_f32_fp8_e32 v[96:97], v73
	v_cvt_pk_f32_fp8_sdwa v[72:73], v73 src0_sel:WORD_1
	v_pk_fma_f32 v[82:83], v[128:129], v[82:83], v[86:87] op_sel:[1,0,0]
	v_pk_fma_f32 v[86:87], v[128:129], v[92:93], v[90:91] op_sel:[1,0,0]
	v_pk_fma_f32 v[90:91], v[128:129], v[96:97], v[94:95] op_sel:[1,0,0]
	v_pk_fma_f32 v[72:73], v[128:129], v[72:73], v[76:77] op_sel:[1,0,0]
	v_cvt_pk_f32_fp8_e32 v[76:77], v74
	v_cvt_pk_f32_fp8_sdwa v[92:93], v74 src0_sel:WORD_1
	v_cvt_pk_f32_fp8_e32 v[94:95], v75
	v_cvt_pk_f32_fp8_sdwa v[74:75], v75 src0_sel:WORD_1
	v_pk_fma_f32 v[76:77], v[128:129], v[76:77], v[80:81] op_sel:[1,0,0]
	v_pk_fma_f32 v[80:81], v[128:129], v[92:93], v[84:85] op_sel:[1,0,0]
	v_pk_fma_f32 v[84:85], v[128:129], v[94:95], v[88:89] op_sel:[1,0,0]
	v_pk_fma_f32 v[74:75], v[128:129], v[74:75], v[78:79] op_sel:[1,0,0]
	v_cvt_pk_f32_fp8_e32 v[78:79], v68
	v_cvt_pk_f32_fp8_sdwa v[88:89], v68 src0_sel:WORD_1
	v_cvt_pk_f32_fp8_e32 v[92:93], v69
	v_cvt_pk_f32_fp8_sdwa v[68:69], v69 src0_sel:WORD_1
	v_pk_fma_f32 v[78:79], v[130:131], v[78:79], v[82:83] op_sel_hi:[0,1,1]
	v_pk_fma_f32 v[82:83], v[130:131], v[88:89], v[86:87] op_sel_hi:[0,1,1]
	v_pk_fma_f32 v[86:87], v[130:131], v[92:93], v[90:91] op_sel_hi:[0,1,1]
	v_pk_fma_f32 v[68:69], v[130:131], v[68:69], v[72:73] op_sel_hi:[0,1,1]
	v_cvt_pk_f32_fp8_e32 v[72:73], v70
	v_cvt_pk_f32_fp8_sdwa v[88:89], v70 src0_sel:WORD_1
	v_cvt_pk_f32_fp8_e32 v[90:91], v71
	v_cvt_pk_f32_fp8_sdwa v[70:71], v71 src0_sel:WORD_1
	v_pk_fma_f32 v[72:73], v[130:131], v[72:73], v[76:77] op_sel_hi:[0,1,1]
	v_pk_fma_f32 v[76:77], v[130:131], v[88:89], v[80:81] op_sel_hi:[0,1,1]
	v_pk_fma_f32 v[80:81], v[130:131], v[90:91], v[84:85] op_sel_hi:[0,1,1]
	v_cvt_pk_f32_fp8_e32 v[84:85], v64
	v_cvt_pk_f32_fp8_sdwa v[88:89], v64 src0_sel:WORD_1
	v_cvt_pk_f32_fp8_e32 v[90:91], v65
	v_cvt_pk_f32_fp8_sdwa v[64:65], v65 src0_sel:WORD_1
	v_pk_fma_f32 v[70:71], v[130:131], v[70:71], v[74:75] op_sel_hi:[0,1,1]
	v_mov_b32_e32 v74, v131
	v_pk_fma_f32 v[78:79], v[74:75], v[84:85], v[78:79] op_sel_hi:[0,1,1]
	v_pk_fma_f32 v[64:65], v[74:75], v[64:65], v[68:69] op_sel_hi:[0,1,1]
	v_cvt_pk_f32_fp8_e32 v[68:69], v66
	v_pk_fma_f32 v[82:83], v[74:75], v[88:89], v[82:83] op_sel_hi:[0,1,1]
	v_pk_fma_f32 v[84:85], v[74:75], v[90:91], v[86:87] op_sel_hi:[0,1,1]
	v_cvt_pk_f32_fp8_sdwa v[86:87], v66 src0_sel:WORD_1
	v_cvt_pk_f32_fp8_e32 v[88:89], v67
	v_cvt_pk_f32_fp8_sdwa v[66:67], v67 src0_sel:WORD_1
	v_pk_fma_f32 v[68:69], v[74:75], v[68:69], v[72:73] op_sel_hi:[0,1,1]
	v_pk_fma_f32 v[72:73], v[74:75], v[86:87], v[76:77] op_sel_hi:[0,1,1]
	v_pk_fma_f32 v[76:77], v[74:75], v[88:89], v[80:81] op_sel_hi:[0,1,1]
	v_pk_fma_f32 v[66:67], v[74:75], v[66:67], v[70:71] op_sel_hi:[0,1,1]
	v_permlane32_swap_b32 v78, v68
	v_permlane32_swap_b32 v79, v69
	v_permlane32_swap_b32 v82, v72
	v_permlane32_swap_b32 v83, v73
	v_permlane32_swap_b32 v84, v76
	v_permlane32_swap_b32 v85, v77
	v_permlane32_swap_b32 v64, v66
	v_permlane32_swap_b32 v65, v67
	v_pk_add_f32 v[68:69], v[78:79], v[68:69]
	v_pk_add_f32 v[70:71], v[82:83], v[72:73]
	v_pk_add_f32 v[72:73], v[84:85], v[76:77]
	v_pk_add_f32 v[64:65], v[64:65], v[66:67]
	s_nop 1
	v_permlane16_swap_b32 v68, v72
	v_permlane16_swap_b32 v69, v73
	v_permlane16_swap_b32 v70, v64
	v_permlane16_swap_b32 v71, v65
	v_pk_add_f32 v[66:67], v[68:69], v[72:73]
	v_pk_add_f32 v[64:65], v[70:71], v[64:65]
	v_and_b32_e32 v89, 0xffff0000, v212
	s_nop 1
	v_add_f32_dpp v64, v64, v64 row_ror:8 row_mask:0xf bank_mask:0xc
	v_add_f32_dpp v64, v66, v66 row_ror:8 row_mask:0xf bank_mask:0x3
	v_add_f32_dpp v65, v65, v65 row_ror:8 row_mask:0xf bank_mask:0xc
	v_add_f32_dpp v65, v67, v67 row_ror:8 row_mask:0xf bank_mask:0x3
	v_and_b32_e32 v91, 0xffff0000, v213
	v_lshlrev_b32_e32 v88, 16, v212
	v_lshlrev_b32_e32 v90, 16, v213
	v_readlane_b32 s98, v248, s59
	v_readlane_b32 s99, v249, s59
	v_pk_fma_f32 v[66:67], v[88:89], s[74:75], v[90:91] op_sel_hi:[1,0,1]
	v_lshlrev_b64 v[92:93], 13, v[186:187]
	v_pk_add_f32 v[66:67], v[66:67], s[98:99] op_sel_hi:[1,0] neg_lo:[0,1] neg_hi:[0,1]
	v_lshl_add_u64 v[70:71], s[78:79], 0, v[92:93]
	v_pk_mul_f32 v[66:67], s[98:99], v[66:67] op_sel:[1,0]
	s_waitcnt lgkmcnt(0)
	ds_bpermute_b32 v64, v250, v64
	ds_bpermute_b32 v65, v250, v65
	v_pk_fma_f32 v[66:67], v[66:67], v[178:179], v[180:181]
	v_lshl_add_u64 v[70:71], v[70:71], 0, v[138:139]
	s_waitcnt lgkmcnt(0)
	v_pk_fma_f32 v[64:65], v[66:67], s[74:75], v[64:65] op_sel_hi:[1,0,1]
	s_add_i32 s16, s16, 16
	s_addk_i32 s17, 0x100
	s_add_i32 s34, s34, 0x40000
	s_and_b64 vcc, exec, s[0:1]
	s_mov_b32 s0, s61
	global_store_dwordx2 v[70:71], v[64:65], off nt
	s_cbranch_vccnz .LBB0_938
.LBB0_934:
	s_add_i32 s15, s17, 0xffffff80
	s_and_b32 s15, s15, 0x780
	v_lshl_add_u32 v76, s15, 2, v189
	ds_read_b128 v[64:67], v76
	s_add_i32 s14, s34, 0xfffc0000
	s_add_i32 s1, s0, 1
	s_and_b32 s14, s14, 0x1e00000
	s_add_u32 s14, s38, s14
	s_waitcnt lgkmcnt(0)
	s_addc_u32 s15, s39, 0
	ds_read_b128 v[68:71], v76 offset:16
	ds_read_b128 v[72:75], v76 offset:32
	ds_read_b128 v[128:131], v76 offset:48
	v_lshl_or_b32 v65, v65, 7, v137
	v_lshl_or_b32 v64, v64, 7, v174
	global_load_dwordx4 v[124:127], v64, s[14:15]
	global_load_dwordx4 v[120:123], v65, s[14:15]
	v_lshl_or_b32 v64, v67, 7, v137
	v_lshl_or_b32 v65, v66, 7, v174
	global_load_dwordx4 v[116:119], v65, s[14:15]
	global_load_dwordx4 v[112:115], v64, s[14:15]
	s_waitcnt lgkmcnt(2)
	v_lshl_or_b32 v64, v69, 7, v137
	v_lshl_or_b32 v65, v68, 7, v174
	global_load_dwordx4 v[108:111], v65, s[14:15]
	global_load_dwordx4 v[104:107], v64, s[14:15]
	v_lshl_or_b32 v64, v71, 7, v137
	v_lshl_or_b32 v65, v70, 7, v174
	global_load_dwordx4 v[100:103], v65, s[14:15]
	global_load_dwordx4 v[96:99], v64, s[14:15]
	s_waitcnt lgkmcnt(1)
	v_lshl_or_b32 v64, v73, 7, v137
	v_lshl_or_b32 v65, v72, 7, v174
	global_load_dwordx4 v[92:95], v65, s[14:15]
	global_load_dwordx4 v[88:91], v64, s[14:15]
	s_and_b32 s59, s1, 15
	v_lshl_or_b32 v64, v75, 7, v137
	v_lshl_or_b32 v65, v74, 7, v174
	s_add_i32 s1, s16, -16
	v_or_b32_e32 v186, s59, v176
	global_load_dwordx4 v[84:87], v65, s[14:15]
	global_load_dwordx4 v[80:83], v64, s[14:15]
	s_waitcnt lgkmcnt(0)
	s_and_b32 s1, s1, 0x780
	v_ashrrev_i32_e32 v187, 31, v186
	v_lshl_or_b32 v64, v129, 7, v137
	v_lshl_or_b32 v65, v128, 7, v174
	v_or_b32_e32 v214, s1, v192
	global_load_dwordx4 v[76:79], v65, s[14:15]
	global_load_dwordx4 v[72:75], v64, s[14:15]
	v_lshlrev_b32_e32 v64, 7, v131
	v_lshlrev_b32_e32 v65, 7, v130
	v_or_b32_e32 v64, v64, v137
	v_or_b32_e32 v65, v65, v174
	s_and_b32 s1, s0, 14
	s_waitcnt vmcnt(30)
	v_cvt_pk_f32_fp8_e32 v[224:225], v0
	v_cvt_pk_f32_fp8_sdwa v[226:227], v0 src0_sel:WORD_1
	v_cvt_pk_f32_fp8_e32 v[228:229], v1
	v_cvt_pk_f32_fp8_sdwa v[230:231], v1 src0_sel:WORD_1
	global_load_dwordx4 v[68:71], v65, s[14:15]
	s_nop 0
	global_load_dwordx4 v[64:67], v64, s[14:15]
	v_lshl_add_u32 v128, s1, 9, v193
	s_waitcnt vmcnt(31)
	v_cvt_pk_f32_fp8_e32 v[240:241], v4
	v_cvt_pk_f32_fp8_sdwa v[242:243], v4 src0_sel:WORD_1
	v_cvt_pk_f32_fp8_e32 v[244:245], v5
	v_cvt_pk_f32_fp8_sdwa v[246:247], v5 src0_sel:WORD_1
	ds_read_b128 v[216:219], v128
	ds_read_b128 v[220:223], v128 offset:16
	ds_read_b128 v[132:135], v128 offset:32
	ds_read_b128 v[128:131], v128 offset:48
	v_cvt_pk_f32_fp8_e32 v[232:233], v2
	s_waitcnt lgkmcnt(3)
	v_pk_fma_f32 v[224:225], v[216:217], v[224:225], 0 op_sel_hi:[0,1,0]
	v_pk_fma_f32 v[226:227], v[216:217], v[226:227], 0 op_sel_hi:[0,1,0]
	v_pk_fma_f32 v[228:229], v[216:217], v[228:229], 0 op_sel_hi:[0,1,0]
	v_pk_fma_f32 v[230:231], v[216:217], v[230:231], 0 op_sel_hi:[0,1,0]
	v_cvt_pk_f32_fp8_sdwa v[234:235], v2 src0_sel:WORD_1
	v_cvt_pk_f32_fp8_e32 v[236:237], v3
	v_cvt_pk_f32_fp8_sdwa v[238:239], v3 src0_sel:WORD_1
	v_pk_fma_f32 v[224:225], v[216:217], v[240:241], v[224:225] op_sel:[1,0,0]
	v_pk_fma_f32 v[226:227], v[216:217], v[242:243], v[226:227] op_sel:[1,0,0]
	v_pk_fma_f32 v[228:229], v[216:217], v[244:245], v[228:229] op_sel:[1,0,0]
	v_pk_fma_f32 v[230:231], v[216:217], v[246:247], v[230:231] op_sel:[1,0,0]
	v_cvt_pk_f32_fp8_e32 v[240:241], v6
	v_cvt_pk_f32_fp8_sdwa v[242:243], v6 src0_sel:WORD_1
	v_cvt_pk_f32_fp8_e32 v[244:245], v7
	v_cvt_pk_f32_fp8_sdwa v[246:247], v7 src0_sel:WORD_1
	v_pk_fma_f32 v[232:233], v[216:217], v[232:233], 0 op_sel_hi:[0,1,0]
	v_pk_fma_f32 v[234:235], v[216:217], v[234:235], 0 op_sel_hi:[0,1,0]
	v_pk_fma_f32 v[236:237], v[216:217], v[236:237], 0 op_sel_hi:[0,1,0]
	v_pk_fma_f32 v[238:239], v[216:217], v[238:239], 0 op_sel_hi:[0,1,0]
	v_pk_fma_f32 v[232:233], v[216:217], v[240:241], v[232:233] op_sel:[1,0,0]
	v_pk_fma_f32 v[234:235], v[216:217], v[242:243], v[234:235] op_sel:[1,0,0]
	v_pk_fma_f32 v[236:237], v[216:217], v[244:245], v[236:237] op_sel:[1,0,0]
	v_pk_fma_f32 v[216:217], v[216:217], v[246:247], v[238:239] op_sel:[1,0,0]
	s_waitcnt vmcnt(30)
	v_cvt_pk_f32_fp8_e32 v[238:239], v8
	v_cvt_pk_f32_fp8_sdwa v[240:241], v8 src0_sel:WORD_1
	v_cvt_pk_f32_fp8_e32 v[242:243], v9
	v_cvt_pk_f32_fp8_sdwa v[244:245], v9 src0_sel:WORD_1
	v_pk_fma_f32 v[224:225], v[218:219], v[238:239], v[224:225] op_sel_hi:[0,1,1]
	v_pk_fma_f32 v[226:227], v[218:219], v[240:241], v[226:227] op_sel_hi:[0,1,1]
	v_pk_fma_f32 v[228:229], v[218:219], v[242:243], v[228:229] op_sel_hi:[0,1,1]
	v_pk_fma_f32 v[230:231], v[218:219], v[244:245], v[230:231] op_sel_hi:[0,1,1]
	v_cvt_pk_f32_fp8_e32 v[238:239], v10
	v_cvt_pk_f32_fp8_sdwa v[240:241], v10 src0_sel:WORD_1
	v_cvt_pk_f32_fp8_e32 v[242:243], v11
	v_cvt_pk_f32_fp8_sdwa v[244:245], v11 src0_sel:WORD_1
	v_pk_fma_f32 v[232:233], v[218:219], v[238:239], v[232:233] op_sel_hi:[0,1,1]
	v_pk_fma_f32 v[234:235], v[218:219], v[240:241], v[234:235] op_sel_hi:[0,1,1]
	v_pk_fma_f32 v[236:237], v[218:219], v[242:243], v[236:237] op_sel_hi:[0,1,1]
	v_pk_fma_f32 v[216:217], v[218:219], v[244:245], v[216:217] op_sel_hi:[0,1,1]
	v_mov_b32_e32 v138, v219
	s_waitcnt vmcnt(29)
	v_cvt_pk_f32_fp8_e32 v[218:219], v12
	v_cvt_pk_f32_fp8_sdwa v[238:239], v12 src0_sel:WORD_1
	v_cvt_pk_f32_fp8_e32 v[240:241], v13
	v_cvt_pk_f32_fp8_sdwa v[242:243], v13 src0_sel:WORD_1
	v_pk_fma_f32 v[218:219], v[138:139], v[218:219], v[224:225] op_sel_hi:[0,1,1]
	v_pk_fma_f32 v[224:225], v[138:139], v[238:239], v[226:227] op_sel_hi:[0,1,1]
	v_pk_fma_f32 v[226:227], v[138:139], v[240:241], v[228:229] op_sel_hi:[0,1,1]
	v_pk_fma_f32 v[228:229], v[138:139], v[242:243], v[230:231] op_sel_hi:[0,1,1]
	v_cvt_pk_f32_fp8_e32 v[230:231], v14
	v_cvt_pk_f32_fp8_sdwa v[238:239], v14 src0_sel:WORD_1
	v_cvt_pk_f32_fp8_e32 v[240:241], v15
	v_cvt_pk_f32_fp8_sdwa v[242:243], v15 src0_sel:WORD_1
	v_pk_fma_f32 v[230:231], v[138:139], v[230:231], v[232:233] op_sel_hi:[0,1,1]
	v_pk_fma_f32 v[232:233], v[138:139], v[238:239], v[234:235] op_sel_hi:[0,1,1]
	v_pk_fma_f32 v[234:235], v[138:139], v[240:241], v[236:237] op_sel_hi:[0,1,1]
	v_pk_fma_f32 v[216:217], v[138:139], v[242:243], v[216:217] op_sel_hi:[0,1,1]
	s_waitcnt vmcnt(28)
	v_cvt_pk_f32_fp8_e32 v[236:237], v16
	v_cvt_pk_f32_fp8_sdwa v[238:239], v16 src0_sel:WORD_1
	v_cvt_pk_f32_fp8_e32 v[240:241], v17
	v_cvt_pk_f32_fp8_sdwa v[242:243], v17 src0_sel:WORD_1
	s_waitcnt lgkmcnt(2)
	v_pk_fma_f32 v[218:219], v[220:221], v[236:237], v[218:219] op_sel_hi:[0,1,1]
	v_pk_fma_f32 v[224:225], v[220:221], v[238:239], v[224:225] op_sel_hi:[0,1,1]
	v_pk_fma_f32 v[226:227], v[220:221], v[240:241], v[226:227] op_sel_hi:[0,1,1]
	v_pk_fma_f32 v[228:229], v[220:221], v[242:243], v[228:229] op_sel_hi:[0,1,1]
	v_cvt_pk_f32_fp8_e32 v[236:237], v18
	v_cvt_pk_f32_fp8_sdwa v[238:239], v18 src0_sel:WORD_1
	v_cvt_pk_f32_fp8_e32 v[240:241], v19
	v_cvt_pk_f32_fp8_sdwa v[242:243], v19 src0_sel:WORD_1
	v_pk_fma_f32 v[230:231], v[220:221], v[236:237], v[230:231] op_sel_hi:[0,1,1]
	v_pk_fma_f32 v[232:233], v[220:221], v[238:239], v[232:233] op_sel_hi:[0,1,1]
	v_pk_fma_f32 v[234:235], v[220:221], v[240:241], v[234:235] op_sel_hi:[0,1,1]
	v_pk_fma_f32 v[216:217], v[220:221], v[242:243], v[216:217] op_sel_hi:[0,1,1]
	s_waitcnt vmcnt(27)
	v_cvt_pk_f32_fp8_e32 v[236:237], v20
	v_cvt_pk_f32_fp8_sdwa v[238:239], v20 src0_sel:WORD_1
	v_cvt_pk_f32_fp8_e32 v[240:241], v21
	v_cvt_pk_f32_fp8_sdwa v[242:243], v21 src0_sel:WORD_1
	v_pk_fma_f32 v[218:219], v[220:221], v[236:237], v[218:219] op_sel:[1,0,0]
	v_pk_fma_f32 v[224:225], v[220:221], v[238:239], v[224:225] op_sel:[1,0,0]
	v_pk_fma_f32 v[226:227], v[220:221], v[240:241], v[226:227] op_sel:[1,0,0]
	v_pk_fma_f32 v[228:229], v[220:221], v[242:243], v[228:229] op_sel:[1,0,0]
	v_cvt_pk_f32_fp8_e32 v[236:237], v22
	v_cvt_pk_f32_fp8_sdwa v[238:239], v22 src0_sel:WORD_1
	v_cvt_pk_f32_fp8_e32 v[240:241], v23
	v_cvt_pk_f32_fp8_sdwa v[242:243], v23 src0_sel:WORD_1
	v_pk_fma_f32 v[230:231], v[220:221], v[236:237], v[230:231] op_sel:[1,0,0]
	v_pk_fma_f32 v[232:233], v[220:221], v[238:239], v[232:233] op_sel:[1,0,0]
	v_pk_fma_f32 v[234:235], v[220:221], v[240:241], v[234:235] op_sel:[1,0,0]
	v_pk_fma_f32 v[216:217], v[220:221], v[242:243], v[216:217] op_sel:[1,0,0]
	s_waitcnt vmcnt(26)
	v_cvt_pk_f32_fp8_e32 v[220:221], v24
	v_cvt_pk_f32_fp8_sdwa v[236:237], v24 src0_sel:WORD_1
	v_cvt_pk_f32_fp8_e32 v[238:239], v25
	v_cvt_pk_f32_fp8_sdwa v[240:241], v25 src0_sel:WORD_1
	v_pk_fma_f32 v[218:219], v[222:223], v[220:221], v[218:219] op_sel_hi:[0,1,1]
	v_pk_fma_f32 v[220:221], v[222:223], v[236:237], v[224:225] op_sel_hi:[0,1,1]
	v_pk_fma_f32 v[224:225], v[222:223], v[238:239], v[226:227] op_sel_hi:[0,1,1]
	v_pk_fma_f32 v[226:227], v[222:223], v[240:241], v[228:229] op_sel_hi:[0,1,1]
	v_cvt_pk_f32_fp8_e32 v[228:229], v26
	v_cvt_pk_f32_fp8_sdwa v[236:237], v26 src0_sel:WORD_1
	v_cvt_pk_f32_fp8_e32 v[238:239], v27
	v_cvt_pk_f32_fp8_sdwa v[240:241], v27 src0_sel:WORD_1
	v_pk_fma_f32 v[228:229], v[222:223], v[228:229], v[230:231] op_sel_hi:[0,1,1]
	v_pk_fma_f32 v[230:231], v[222:223], v[236:237], v[232:233] op_sel_hi:[0,1,1]
	v_pk_fma_f32 v[232:233], v[222:223], v[238:239], v[234:235] op_sel_hi:[0,1,1]
	v_pk_fma_f32 v[216:217], v[222:223], v[240:241], v[216:217] op_sel_hi:[0,1,1]
	v_mov_b32_e32 v138, v223
	s_waitcnt vmcnt(25)
	v_cvt_pk_f32_fp8_e32 v[222:223], v28
	v_cvt_pk_f32_fp8_sdwa v[234:235], v28 src0_sel:WORD_1
	v_cvt_pk_f32_fp8_e32 v[236:237], v29
	v_cvt_pk_f32_fp8_sdwa v[238:239], v29 src0_sel:WORD_1
	v_pk_fma_f32 v[218:219], v[138:139], v[222:223], v[218:219] op_sel_hi:[0,1,1]
	v_pk_fma_f32 v[220:221], v[138:139], v[234:235], v[220:221] op_sel_hi:[0,1,1]
	v_pk_fma_f32 v[222:223], v[138:139], v[236:237], v[224:225] op_sel_hi:[0,1,1]
	v_pk_fma_f32 v[224:225], v[138:139], v[238:239], v[226:227] op_sel_hi:[0,1,1]
	v_cvt_pk_f32_fp8_e32 v[226:227], v30
	v_cvt_pk_f32_fp8_sdwa v[234:235], v30 src0_sel:WORD_1
	v_cvt_pk_f32_fp8_e32 v[236:237], v31
	v_cvt_pk_f32_fp8_sdwa v[238:239], v31 src0_sel:WORD_1
	v_pk_fma_f32 v[226:227], v[138:139], v[226:227], v[228:229] op_sel_hi:[0,1,1]
	v_pk_fma_f32 v[228:229], v[138:139], v[234:235], v[230:231] op_sel_hi:[0,1,1]
	v_pk_fma_f32 v[230:231], v[138:139], v[236:237], v[232:233] op_sel_hi:[0,1,1]
	v_pk_fma_f32 v[216:217], v[138:139], v[238:239], v[216:217] op_sel_hi:[0,1,1]
	s_waitcnt vmcnt(24)
	v_cvt_pk_f32_fp8_e32 v[232:233], v32
	v_cvt_pk_f32_fp8_sdwa v[234:235], v32 src0_sel:WORD_1
	v_cvt_pk_f32_fp8_e32 v[236:237], v33
	v_cvt_pk_f32_fp8_sdwa v[238:239], v33 src0_sel:WORD_1
	s_waitcnt lgkmcnt(1)
	v_pk_fma_f32 v[218:219], v[132:133], v[232:233], v[218:219] op_sel_hi:[0,1,1]
	v_pk_fma_f32 v[220:221], v[132:133], v[234:235], v[220:221] op_sel_hi:[0,1,1]
	v_pk_fma_f32 v[222:223], v[132:133], v[236:237], v[222:223] op_sel_hi:[0,1,1]
	v_pk_fma_f32 v[224:225], v[132:133], v[238:239], v[224:225] op_sel_hi:[0,1,1]
	v_cvt_pk_f32_fp8_e32 v[232:233], v34
	v_cvt_pk_f32_fp8_sdwa v[234:235], v34 src0_sel:WORD_1
	v_cvt_pk_f32_fp8_e32 v[236:237], v35
	v_cvt_pk_f32_fp8_sdwa v[238:239], v35 src0_sel:WORD_1
	v_pk_fma_f32 v[226:227], v[132:133], v[232:233], v[226:227] op_sel_hi:[0,1,1]
	v_pk_fma_f32 v[228:229], v[132:133], v[234:235], v[228:229] op_sel_hi:[0,1,1]
	v_pk_fma_f32 v[230:231], v[132:133], v[236:237], v[230:231] op_sel_hi:[0,1,1]
	v_pk_fma_f32 v[216:217], v[132:133], v[238:239], v[216:217] op_sel_hi:[0,1,1]
	s_waitcnt vmcnt(23)
	v_cvt_pk_f32_fp8_e32 v[232:233], v36
	v_cvt_pk_f32_fp8_sdwa v[234:235], v36 src0_sel:WORD_1
	v_cvt_pk_f32_fp8_e32 v[236:237], v37
	v_cvt_pk_f32_fp8_sdwa v[238:239], v37 src0_sel:WORD_1
	v_pk_fma_f32 v[218:219], v[132:133], v[232:233], v[218:219] op_sel:[1,0,0]
	v_pk_fma_f32 v[220:221], v[132:133], v[234:235], v[220:221] op_sel:[1,0,0]
	v_pk_fma_f32 v[222:223], v[132:133], v[236:237], v[222:223] op_sel:[1,0,0]
	v_pk_fma_f32 v[224:225], v[132:133], v[238:239], v[224:225] op_sel:[1,0,0]
	v_cvt_pk_f32_fp8_e32 v[232:233], v38
	v_cvt_pk_f32_fp8_sdwa v[234:235], v38 src0_sel:WORD_1
	v_cvt_pk_f32_fp8_e32 v[236:237], v39
	v_cvt_pk_f32_fp8_sdwa v[238:239], v39 src0_sel:WORD_1
	v_pk_fma_f32 v[226:227], v[132:133], v[232:233], v[226:227] op_sel:[1,0,0]
	v_pk_fma_f32 v[228:229], v[132:133], v[234:235], v[228:229] op_sel:[1,0,0]
	v_pk_fma_f32 v[230:231], v[132:133], v[236:237], v[230:231] op_sel:[1,0,0]
	v_pk_fma_f32 v[132:133], v[132:133], v[238:239], v[216:217] op_sel:[1,0,0]
	s_waitcnt vmcnt(22)
	v_cvt_pk_f32_fp8_e32 v[216:217], v40
	v_cvt_pk_f32_fp8_sdwa v[232:233], v40 src0_sel:WORD_1
	v_cvt_pk_f32_fp8_e32 v[234:235], v41
	v_cvt_pk_f32_fp8_sdwa v[236:237], v41 src0_sel:WORD_1
	v_pk_fma_f32 v[216:217], v[134:135], v[216:217], v[218:219] op_sel_hi:[0,1,1]
	v_pk_fma_f32 v[218:219], v[134:135], v[232:233], v[220:221] op_sel_hi:[0,1,1]
	v_pk_fma_f32 v[220:221], v[134:135], v[234:235], v[222:223] op_sel_hi:[0,1,1]
	v_pk_fma_f32 v[222:223], v[134:135], v[236:237], v[224:225] op_sel_hi:[0,1,1]
	v_cvt_pk_f32_fp8_e32 v[224:225], v42
	v_cvt_pk_f32_fp8_sdwa v[232:233], v42 src0_sel:WORD_1
	v_cvt_pk_f32_fp8_e32 v[234:235], v43
	v_cvt_pk_f32_fp8_sdwa v[236:237], v43 src0_sel:WORD_1
	v_pk_fma_f32 v[224:225], v[134:135], v[224:225], v[226:227] op_sel_hi:[0,1,1]
	v_pk_fma_f32 v[226:227], v[134:135], v[232:233], v[228:229] op_sel_hi:[0,1,1]
	v_pk_fma_f32 v[228:229], v[134:135], v[234:235], v[230:231] op_sel_hi:[0,1,1]
	v_pk_fma_f32 v[132:133], v[134:135], v[236:237], v[132:133] op_sel_hi:[0,1,1]
	s_waitcnt vmcnt(21)
	v_cvt_pk_f32_fp8_e32 v[230:231], v44
	v_cvt_pk_f32_fp8_sdwa v[232:233], v44 src0_sel:WORD_1
	v_cvt_pk_f32_fp8_e32 v[234:235], v45
	v_cvt_pk_f32_fp8_sdwa v[236:237], v45 src0_sel:WORD_1
	v_mov_b32_e32 v134, v135
	v_pk_fma_f32 v[216:217], v[134:135], v[230:231], v[216:217] op_sel_hi:[0,1,1]
	v_pk_fma_f32 v[218:219], v[134:135], v[232:233], v[218:219] op_sel_hi:[0,1,1]
	v_pk_fma_f32 v[220:221], v[134:135], v[234:235], v[220:221] op_sel_hi:[0,1,1]
	v_pk_fma_f32 v[222:223], v[134:135], v[236:237], v[222:223] op_sel_hi:[0,1,1]
	v_cvt_pk_f32_fp8_e32 v[230:231], v46
	v_cvt_pk_f32_fp8_sdwa v[232:233], v46 src0_sel:WORD_1
	v_cvt_pk_f32_fp8_e32 v[234:235], v47
	v_cvt_pk_f32_fp8_sdwa v[236:237], v47 src0_sel:WORD_1
	v_pk_fma_f32 v[224:225], v[134:135], v[230:231], v[224:225] op_sel_hi:[0,1,1]
	v_pk_fma_f32 v[226:227], v[134:135], v[232:233], v[226:227] op_sel_hi:[0,1,1]
	v_pk_fma_f32 v[228:229], v[134:135], v[234:235], v[228:229] op_sel_hi:[0,1,1]
	v_pk_fma_f32 v[132:133], v[134:135], v[236:237], v[132:133] op_sel_hi:[0,1,1]
	s_waitcnt vmcnt(20)
	v_cvt_pk_f32_fp8_e32 v[134:135], v48
	v_cvt_pk_f32_fp8_sdwa v[230:231], v48 src0_sel:WORD_1
	v_cvt_pk_f32_fp8_e32 v[232:233], v49
	v_cvt_pk_f32_fp8_sdwa v[234:235], v49 src0_sel:WORD_1
	s_waitcnt lgkmcnt(0)
	v_pk_fma_f32 v[134:135], v[128:129], v[134:135], v[216:217] op_sel_hi:[0,1,1]
	v_pk_fma_f32 v[216:217], v[128:129], v[230:231], v[218:219] op_sel_hi:[0,1,1]
	v_pk_fma_f32 v[218:219], v[128:129], v[232:233], v[220:221] op_sel_hi:[0,1,1]
	v_pk_fma_f32 v[220:221], v[128:129], v[234:235], v[222:223] op_sel_hi:[0,1,1]
	v_cvt_pk_f32_fp8_e32 v[222:223], v50
	v_cvt_pk_f32_fp8_sdwa v[230:231], v50 src0_sel:WORD_1
	v_cvt_pk_f32_fp8_e32 v[232:233], v51
	v_cvt_pk_f32_fp8_sdwa v[234:235], v51 src0_sel:WORD_1
	v_pk_fma_f32 v[222:223], v[128:129], v[222:223], v[224:225] op_sel_hi:[0,1,1]
	v_pk_fma_f32 v[224:225], v[128:129], v[230:231], v[226:227] op_sel_hi:[0,1,1]
	v_pk_fma_f32 v[226:227], v[128:129], v[232:233], v[228:229] op_sel_hi:[0,1,1]
	v_pk_fma_f32 v[132:133], v[128:129], v[234:235], v[132:133] op_sel_hi:[0,1,1]
	s_waitcnt vmcnt(19)
	v_cvt_pk_f32_fp8_e32 v[228:229], v52
	v_cvt_pk_f32_fp8_sdwa v[230:231], v52 src0_sel:WORD_1
	v_cvt_pk_f32_fp8_e32 v[232:233], v53
	v_cvt_pk_f32_fp8_sdwa v[234:235], v53 src0_sel:WORD_1
	v_pk_fma_f32 v[134:135], v[128:129], v[228:229], v[134:135] op_sel:[1,0,0]
	v_pk_fma_f32 v[216:217], v[128:129], v[230:231], v[216:217] op_sel:[1,0,0]
	v_pk_fma_f32 v[218:219], v[128:129], v[232:233], v[218:219] op_sel:[1,0,0]
	v_pk_fma_f32 v[220:221], v[128:129], v[234:235], v[220:221] op_sel:[1,0,0]
	v_cvt_pk_f32_fp8_e32 v[228:229], v54
	v_cvt_pk_f32_fp8_sdwa v[230:231], v54 src0_sel:WORD_1
	v_cvt_pk_f32_fp8_e32 v[232:233], v55
	v_cvt_pk_f32_fp8_sdwa v[234:235], v55 src0_sel:WORD_1
	v_pk_fma_f32 v[222:223], v[128:129], v[228:229], v[222:223] op_sel:[1,0,0]
	v_pk_fma_f32 v[224:225], v[128:129], v[230:231], v[224:225] op_sel:[1,0,0]
	v_pk_fma_f32 v[226:227], v[128:129], v[232:233], v[226:227] op_sel:[1,0,0]
	v_pk_fma_f32 v[128:129], v[128:129], v[234:235], v[132:133] op_sel:[1,0,0]
	s_waitcnt vmcnt(18)
	v_cvt_pk_f32_fp8_e32 v[132:133], v56
	v_cvt_pk_f32_fp8_sdwa v[228:229], v56 src0_sel:WORD_1
	v_cvt_pk_f32_fp8_e32 v[230:231], v57
	v_cvt_pk_f32_fp8_sdwa v[232:233], v57 src0_sel:WORD_1
	v_pk_fma_f32 v[132:133], v[130:131], v[132:133], v[134:135] op_sel_hi:[0,1,1]
	v_pk_fma_f32 v[134:135], v[130:131], v[228:229], v[216:217] op_sel_hi:[0,1,1]
	v_pk_fma_f32 v[216:217], v[130:131], v[230:231], v[218:219] op_sel_hi:[0,1,1]
	v_pk_fma_f32 v[218:219], v[130:131], v[232:233], v[220:221] op_sel_hi:[0,1,1]
	v_cvt_pk_f32_fp8_e32 v[220:221], v58
	v_cvt_pk_f32_fp8_sdwa v[228:229], v58 src0_sel:WORD_1
	v_cvt_pk_f32_fp8_e32 v[230:231], v59
	v_cvt_pk_f32_fp8_sdwa v[232:233], v59 src0_sel:WORD_1
	v_pk_fma_f32 v[220:221], v[130:131], v[220:221], v[222:223] op_sel_hi:[0,1,1]
	v_pk_fma_f32 v[222:223], v[130:131], v[228:229], v[224:225] op_sel_hi:[0,1,1]
	s_waitcnt vmcnt(17)
	s_and_b32 s101, s1, 3
	v_lshl_add_u32 v253, s101, 8, v252
	ds_read_b32 v210, v253
	ds_read_b32 v211, v253 offset:1024
	v_cvt_pk_f32_fp8_sdwa v[228:229], v60 src0_sel:WORD_1
	v_pk_fma_f32 v[224:225], v[130:131], v[230:231], v[226:227] op_sel_hi:[0,1,1]
	v_cvt_pk_f32_fp8_e32 v[226:227], v60
	v_cvt_pk_f32_fp8_e32 v[230:231], v61
	v_pk_fma_f32 v[128:129], v[130:131], v[232:233], v[128:129] op_sel_hi:[0,1,1]
	v_mov_b32_e32 v130, v131
	v_cvt_pk_f32_fp8_sdwa v[232:233], v61 src0_sel:WORD_1
	v_pk_fma_f32 v[134:135], v[130:131], v[228:229], v[134:135] op_sel_hi:[0,1,1]
	v_cvt_pk_f32_fp8_sdwa v[228:229], v62 src0_sel:WORD_1
	v_pk_fma_f32 v[132:133], v[130:131], v[226:227], v[132:133] op_sel_hi:[0,1,1]
	v_pk_fma_f32 v[216:217], v[130:131], v[230:231], v[216:217] op_sel_hi:[0,1,1]
	v_cvt_pk_f32_fp8_e32 v[226:227], v62
	v_cvt_pk_f32_fp8_e32 v[230:231], v63
	v_pk_fma_f32 v[218:219], v[130:131], v[232:233], v[218:219] op_sel_hi:[0,1,1]
	v_cvt_pk_f32_fp8_sdwa v[232:233], v63 src0_sel:WORD_1
	v_pk_fma_f32 v[222:223], v[130:131], v[228:229], v[222:223] op_sel_hi:[0,1,1]
	v_pk_fma_f32 v[220:221], v[130:131], v[226:227], v[220:221] op_sel_hi:[0,1,1]
	v_pk_fma_f32 v[224:225], v[130:131], v[230:231], v[224:225] op_sel_hi:[0,1,1]
	v_pk_fma_f32 v[128:129], v[130:131], v[232:233], v[128:129] op_sel_hi:[0,1,1]
	v_permlane32_swap_b32 v134, v222
	v_permlane32_swap_b32 v135, v223
	v_permlane32_swap_b32 v132, v220
	v_permlane32_swap_b32 v133, v221
	v_permlane32_swap_b32 v216, v224
	v_permlane32_swap_b32 v217, v225
	v_permlane32_swap_b32 v218, v128
	v_permlane32_swap_b32 v219, v129
	v_pk_add_f32 v[130:131], v[132:133], v[220:221]
	v_pk_add_f32 v[132:133], v[134:135], v[222:223]
	v_pk_add_f32 v[134:135], v[216:217], v[224:225]
	v_pk_add_f32 v[128:129], v[218:219], v[128:129]
	s_nop 1
	v_permlane16_swap_b32 v130, v134
	v_permlane16_swap_b32 v131, v135
	v_permlane16_swap_b32 v132, v128
	v_permlane16_swap_b32 v133, v129
	v_pk_add_f32 v[130:131], v[130:131], v[134:135]
	v_pk_add_f32 v[132:133], v[132:133], v[128:129]
	s_cmp_lg_u32 s1, 0
	s_nop 1
	v_add_f32_dpp v128, v130, v130 row_ror:8 row_mask:0xf bank_mask:0x3
	v_add_f32_dpp v128, v132, v132 row_ror:8 row_mask:0xf bank_mask:0xc
	v_add_f32_dpp v129, v131, v131 row_ror:8 row_mask:0xf bank_mask:0x3
	v_add_f32_dpp v129, v133, v133 row_ror:8 row_mask:0xf bank_mask:0xc
	v_lshlrev_b32_e32 v138, 2, v214
	s_cbranch_scc1 .LBB0_936
	global_load_dwordx2 v[178:179], v138, s[46:47]
	global_load_dwordx2 v[180:181], v138, s[48:49]
.LBB0_936:
	s_waitcnt lgkmcnt(0)
	v_lshlrev_b32_e32 v132, 16, v210
	v_and_b32_e32 v133, 0xffff0000, v210
	v_lshlrev_b32_e32 v134, 16, v211
	v_and_b32_e32 v135, 0xffff0000, v211
	v_readlane_b32 s98, v248, s1
	v_readlane_b32 s99, v249, s1
	v_or_b32_e32 v214, s1, v176
	s_waitcnt lgkmcnt(0)
	ds_bpermute_b32 v128, v250, v128
	ds_bpermute_b32 v129, v250, v129
	v_pk_fma_f32 v[130:131], v[132:133], s[74:75], v[134:135] op_sel_hi:[1,0,1]
	v_ashrrev_i32_e32 v215, 31, v214
	v_pk_add_f32 v[130:131], v[130:131], s[98:99] op_sel_hi:[1,0] neg_lo:[0,1] neg_hi:[0,1]
	s_add_i32 s61, s0, 2
	v_lshlrev_b64 v[214:215], 13, v[214:215]
	v_pk_mul_f32 v[130:131], s[98:99], v[130:131] op_sel:[1,0]
	s_cmpk_gt_u32 s0, 0xfd
	v_lshl_add_u64 v[214:215], s[78:79], 0, v[214:215]
	s_waitcnt vmcnt(0)
	v_pk_fma_f32 v[130:131], v[130:131], v[178:179], v[180:181]
	s_cselect_b64 s[0:1], -1, 0
	v_lshl_add_u64 v[214:215], v[214:215], 0, v[138:139]
	s_waitcnt lgkmcnt(0)
	v_pk_fma_f32 v[128:129], v[130:131], s[74:75], v[128:129] op_sel_hi:[1,0,1]
	s_and_b64 vcc, exec, s[0:1]
	global_store_dwordx2 v[214:215], v[128:129], off nt
	s_cbranch_vccnz .LBB0_933
	s_and_b32 s15, s17, 0x700
	v_lshl_add_u32 v0, s15, 2, v189
	ds_read_b128 v[6:9], v0
	ds_read_b128 v[22:25], v0 offset:16
	ds_read_b128 v[38:41], v0 offset:32
	ds_read_b128 v[54:57], v0 offset:48
	s_and_b32 s14, s34, 0x3e00000
	s_add_u32 s14, s38, s14
	s_waitcnt lgkmcnt(2)
	s_waitcnt lgkmcnt(1)
	s_waitcnt lgkmcnt(0)
	s_addc_u32 s15, s39, 0
	v_lshl_or_b32 v4, v7, 7, v137
	v_lshl_or_b32 v0, v6, 7, v174
	v_lshl_or_b32 v12, v9, 7, v137
	v_lshl_or_b32 v8, v8, 7, v174
	v_lshl_or_b32 v20, v23, 7, v137
	v_lshl_or_b32 v16, v22, 7, v174
	v_lshl_or_b32 v28, v25, 7, v137
	v_lshl_or_b32 v24, v24, 7, v174
	v_lshl_or_b32 v36, v39, 7, v137
	v_lshl_or_b32 v32, v38, 7, v174
	v_lshl_or_b32 v44, v41, 7, v137
	v_lshl_or_b32 v40, v40, 7, v174
	v_lshl_or_b32 v52, v55, 7, v137
	v_lshl_or_b32 v48, v54, 7, v174
	v_lshl_or_b32 v60, v57, 7, v137
	v_lshl_or_b32 v56, v56, 7, v174
	global_load_dwordx4 v[0:3], v0, s[14:15]
	s_nop 0
	global_load_dwordx4 v[4:7], v4, s[14:15]
	s_nop 0
	global_load_dwordx4 v[8:11], v8, s[14:15]
	s_nop 0
	global_load_dwordx4 v[12:15], v12, s[14:15]
	s_nop 0
	global_load_dwordx4 v[16:19], v16, s[14:15]
	s_nop 0
	global_load_dwordx4 v[20:23], v20, s[14:15]
	s_nop 0
	global_load_dwordx4 v[24:27], v24, s[14:15]
	s_nop 0
	global_load_dwordx4 v[28:31], v28, s[14:15]
	s_nop 0
	global_load_dwordx4 v[32:35], v32, s[14:15]
	s_nop 0
	global_load_dwordx4 v[36:39], v36, s[14:15]
	s_nop 0
	global_load_dwordx4 v[40:43], v40, s[14:15]
	s_nop 0
	global_load_dwordx4 v[44:47], v44, s[14:15]
	s_nop 0
	global_load_dwordx4 v[48:51], v48, s[14:15]
	s_nop 0
	global_load_dwordx4 v[52:55], v52, s[14:15]
	s_nop 0
	global_load_dwordx4 v[56:59], v56, s[14:15]
	s_nop 0
	global_load_dwordx4 v[60:63], v60, s[14:15]
	s_branch .LBB0_933
